# attention phase start: QK-norm gain scan issues its 48 uniform loads at once; unit epilogue waits only for its z loads (vmcnt 16), not the next unit's prefetch DMAs
# speedup vs baseline: 1.0111x; 1.0111x over previous
; __device__ __forceinline__ void phase_attn(const Args& a, int l, LAS unsigned char* lds, int vcu, int G, int wv) {
;     ...
;     { const float* gq = a.qn_gain + (size_t)l * 96; const float* gk = a.kn_gain + (size_t)l * 96;
;       float mq = 0.f, mk = 0.f;
;       for (int i = 0; i < 96; ++i) { mq = fmaxf(mq, fabsf(gq[i])); mk = fmaxf(mk, fabsf(gk[i])); }
;       kb = 1.01f * 9.7979590f * mk;
;       const float hi = kb * 9.7979590f * mq * QSCALE;
;       if (!(hi < 48.f)) kb = -1.f; }
.LBB0_18:
	global_load_dwordx4 v[4:7], v1, s[2:3]
	global_load_dwordx4 v[8:11], v1, s[2:3] offset:16
	global_load_dwordx4 v[12:15], v1, s[2:3] offset:32
	global_load_dwordx4 v[20:23], v1, s[2:3] offset:48
	global_load_dwordx4 v[24:27], v1, s[2:3] offset:64
	global_load_dwordx4 v[28:31], v1, s[2:3] offset:80
	global_load_dwordx4 v[32:35], v1, s[2:3] offset:96
	global_load_dwordx4 v[36:39], v1, s[2:3] offset:112
	global_load_dwordx4 v[40:43], v1, s[2:3] offset:128
	global_load_dwordx4 v[44:47], v1, s[2:3] offset:144
	global_load_dwordx4 v[48:51], v1, s[2:3] offset:160
	global_load_dwordx4 v[52:55], v1, s[2:3] offset:176
	global_load_dwordx4 v[56:59], v1, s[2:3] offset:192
	global_load_dwordx4 v[60:63], v1, s[2:3] offset:208
	global_load_dwordx4 v[64:67], v1, s[2:3] offset:224
	global_load_dwordx4 v[68:71], v1, s[2:3] offset:240
	global_load_dwordx4 v[72:75], v1, s[2:3] offset:256
	global_load_dwordx4 v[76:79], v1, s[2:3] offset:272
	global_load_dwordx4 v[80:83], v1, s[2:3] offset:288
	global_load_dwordx4 v[84:87], v1, s[2:3] offset:304
	global_load_dwordx4 v[88:91], v1, s[2:3] offset:320
	global_load_dwordx4 v[92:95], v1, s[2:3] offset:336
	global_load_dwordx4 v[96:99], v1, s[2:3] offset:352
	global_load_dwordx4 v[100:103], v1, s[2:3] offset:368
	global_load_dwordx4 v[104:107], v1, s[4:5]
	global_load_dwordx4 v[108:111], v1, s[4:5] offset:16
	global_load_dwordx4 v[112:115], v1, s[4:5] offset:32
	global_load_dwordx4 v[116:119], v1, s[4:5] offset:48
	global_load_dwordx4 v[120:123], v1, s[4:5] offset:64
	global_load_dwordx4 v[144:147], v1, s[4:5] offset:80
	global_load_dwordx4 v[148:151], v1, s[4:5] offset:96
	global_load_dwordx4 v[152:155], v1, s[4:5] offset:112
	global_load_dwordx4 v[156:159], v1, s[4:5] offset:128
	global_load_dwordx4 v[160:163], v1, s[4:5] offset:144
	global_load_dwordx4 v[164:167], v1, s[4:5] offset:160
	global_load_dwordx4 v[168:171], v1, s[4:5] offset:176
	global_load_dwordx4 v[172:175], v1, s[4:5] offset:192
	global_load_dwordx4 v[176:179], v1, s[4:5] offset:208
	global_load_dwordx4 v[180:183], v1, s[4:5] offset:224
	global_load_dwordx4 v[184:187], v1, s[4:5] offset:240
	global_load_dwordx4 v[188:191], v1, s[4:5] offset:256
	global_load_dwordx4 v[192:195], v1, s[4:5] offset:272
	global_load_dwordx4 v[196:199], v1, s[4:5] offset:288
	global_load_dwordx4 v[200:203], v1, s[4:5] offset:304
	global_load_dwordx4 v[204:207], v1, s[4:5] offset:320
	global_load_dwordx4 v[208:211], v1, s[4:5] offset:336
	global_load_dwordx4 v[212:215], v1, s[4:5] offset:352
	global_load_dwordx4 v[216:219], v1, s[4:5] offset:368
	s_waitcnt vmcnt(40)
	v_max3_f32 v0, v0, |v4|, |v5|
	v_max3_f32 v0, v0, |v6|, |v7|
	v_max3_f32 v0, v0, |v8|, |v9|
	v_max3_f32 v0, v0, |v10|, |v11|
	v_max3_f32 v0, v0, |v12|, |v13|
	v_max3_f32 v0, v0, |v14|, |v15|
	v_max3_f32 v0, v0, |v20|, |v21|
	v_max3_f32 v0, v0, |v22|, |v23|
	v_max3_f32 v0, v0, |v24|, |v25|
	v_max3_f32 v0, v0, |v26|, |v27|
	v_max3_f32 v0, v0, |v28|, |v29|
	v_max3_f32 v0, v0, |v30|, |v31|
	v_max3_f32 v0, v0, |v32|, |v33|
	v_max3_f32 v0, v0, |v34|, |v35|
	v_max3_f32 v0, v0, |v36|, |v37|
	v_max3_f32 v0, v0, |v38|, |v39|
	s_waitcnt vmcnt(32)
	v_max3_f32 v0, v0, |v40|, |v41|
	v_max3_f32 v0, v0, |v42|, |v43|
	v_max3_f32 v0, v0, |v44|, |v45|
	v_max3_f32 v0, v0, |v46|, |v47|
	v_max3_f32 v0, v0, |v48|, |v49|
	v_max3_f32 v0, v0, |v50|, |v51|
	v_max3_f32 v0, v0, |v52|, |v53|
	v_max3_f32 v0, v0, |v54|, |v55|
	v_max3_f32 v0, v0, |v56|, |v57|
	v_max3_f32 v0, v0, |v58|, |v59|
	v_max3_f32 v0, v0, |v60|, |v61|
	v_max3_f32 v0, v0, |v62|, |v63|
	v_max3_f32 v0, v0, |v64|, |v65|
	v_max3_f32 v0, v0, |v66|, |v67|
	v_max3_f32 v0, v0, |v68|, |v69|
	v_max3_f32 v0, v0, |v70|, |v71|
	s_waitcnt vmcnt(24)
	v_max3_f32 v0, v0, |v72|, |v73|
	v_max3_f32 v0, v0, |v74|, |v75|
	v_max3_f32 v0, v0, |v76|, |v77|
	v_max3_f32 v0, v0, |v78|, |v79|
	v_max3_f32 v0, v0, |v80|, |v81|
	v_max3_f32 v0, v0, |v82|, |v83|
	v_max3_f32 v0, v0, |v84|, |v85|
	v_max3_f32 v0, v0, |v86|, |v87|
	v_max3_f32 v0, v0, |v88|, |v89|
	v_max3_f32 v0, v0, |v90|, |v91|
	v_max3_f32 v0, v0, |v92|, |v93|
	v_max3_f32 v0, v0, |v94|, |v95|
	v_max3_f32 v0, v0, |v96|, |v97|
	v_max3_f32 v0, v0, |v98|, |v99|
	v_max3_f32 v0, v0, |v100|, |v101|
	v_max3_f32 v0, v0, |v102|, |v103|
	s_waitcnt vmcnt(16)
	v_max3_f32 v2, v2, |v104|, |v105|
	v_max3_f32 v2, v2, |v106|, |v107|
	v_max3_f32 v2, v2, |v108|, |v109|
	v_max3_f32 v2, v2, |v110|, |v111|
	v_max3_f32 v2, v2, |v112|, |v113|
	v_max3_f32 v2, v2, |v114|, |v115|
	v_max3_f32 v2, v2, |v116|, |v117|
	v_max3_f32 v2, v2, |v118|, |v119|
	v_max3_f32 v2, v2, |v120|, |v121|
	v_max3_f32 v2, v2, |v122|, |v123|
	v_max3_f32 v2, v2, |v144|, |v145|
	v_max3_f32 v2, v2, |v146|, |v147|
	v_max3_f32 v2, v2, |v148|, |v149|
	v_max3_f32 v2, v2, |v150|, |v151|
	v_max3_f32 v2, v2, |v152|, |v153|
	v_max3_f32 v2, v2, |v154|, |v155|
	s_waitcnt vmcnt(8)
	v_max3_f32 v2, v2, |v156|, |v157|
	v_max3_f32 v2, v2, |v158|, |v159|
	v_max3_f32 v2, v2, |v160|, |v161|
	v_max3_f32 v2, v2, |v162|, |v163|
	v_max3_f32 v2, v2, |v164|, |v165|
	v_max3_f32 v2, v2, |v166|, |v167|
	v_max3_f32 v2, v2, |v168|, |v169|
	v_max3_f32 v2, v2, |v170|, |v171|
	v_max3_f32 v2, v2, |v172|, |v173|
	v_max3_f32 v2, v2, |v174|, |v175|
	v_max3_f32 v2, v2, |v176|, |v177|
	v_max3_f32 v2, v2, |v178|, |v179|
	v_max3_f32 v2, v2, |v180|, |v181|
	v_max3_f32 v2, v2, |v182|, |v183|
	v_max3_f32 v2, v2, |v184|, |v185|
	v_max3_f32 v2, v2, |v186|, |v187|
	s_waitcnt vmcnt(0)
	v_max3_f32 v2, v2, |v188|, |v189|
	v_max3_f32 v2, v2, |v190|, |v191|
	v_max3_f32 v2, v2, |v192|, |v193|
	v_max3_f32 v2, v2, |v194|, |v195|
	v_max3_f32 v2, v2, |v196|, |v197|
	v_max3_f32 v2, v2, |v198|, |v199|
	v_max3_f32 v2, v2, |v200|, |v201|
	v_max3_f32 v2, v2, |v202|, |v203|
	v_max3_f32 v2, v2, |v204|, |v205|
	v_max3_f32 v2, v2, |v206|, |v207|
	v_max3_f32 v2, v2, |v208|, |v209|
	v_max3_f32 v2, v2, |v210|, |v211|
	v_max3_f32 v2, v2, |v212|, |v213|
	v_max3_f32 v2, v2, |v214|, |v215|
	v_max3_f32 v2, v2, |v216|, |v217|
	v_max3_f32 v2, v2, |v218|, |v219|
	v_readlane_b32 s0, v252, 7
	v_readlane_b32 s1, v252, 8
	s_mov_b32 s12, 0
	s_and_b64 vcc, exec, s[0:1]
	s_cbranch_vccz .LBB0_21
	v_readlane_b32 s12, v253, 29

; __device__ __forceinline__ void attn_unit(const Args& a, int l, int b, int h, int R0, bool special, LAS unsigned char* lds, float kb, int wv, bool pre, bool hasn, int nb, int nh, int nR0) {
;     ...
;     const bool st = !(special && wave >= 4);
;     bf16_t* prow = proj + (size_t)mq * PW + h * 64 + (hi ? 8 : 0);
;     u32x4 zw[4];
;     if (st) {
; #pragma unroll
;         for (int k = 0; k < 4; ++k) zw[k] = *(const u32x4*)(prow + C_ZM + 16 * k);
;     }
;     if (hasn) ATT_REQUEST(nb, nh, nR0);
.LBB0_196:
	s_mul_i32 s6, s57, 0x2080
	s_add_i32 s6, s6, s62
	s_mul_i32 s90, s58, 0x60
	s_add_i32 s6, s6, s64
	s_lshl_b64 s[16:17], s[90:91], 1
	s_mov_b32 s18, 0x15555556
	s_add_u32 s16, s50, s16
	v_mul_hi_u32 v0, v181, s18
	s_addc_u32 s17, s51, s17
	v_mul_i32_i24_e32 v28, -12, v0
	v_add_u32_e32 v0, s6, v0
	v_mov_b64_e32 v[24:25], s[16:17]
	s_movk_i32 s7, 0x600
	v_add_lshl_u32 v28, v28, v181, 3
	v_mad_i64_i32 v[26:27], s[16:17], v0, s7, v[24:25]
	v_ashrrev_i32_e32 v29, 31, v28
	v_mul_hi_u32 v0, v184, s18
	v_lshl_add_u64 v[26:27], v[28:29], 1, v[26:27]
	v_mul_i32_i24_e32 v28, -12, v0
	s_mov_b32 m0, s63
	v_add_u32_e32 v0, s6, v0
	v_add_lshl_u32 v28, v28, v184, 3
	global_load_lds_dwordx4 v[26:27], off
	v_mad_i64_i32 v[26:27], s[16:17], v0, s7, v[24:25]
	v_ashrrev_i32_e32 v29, 31, v28
	v_mul_hi_u32 v0, v183, s18
	v_lshl_add_u64 v[26:27], v[28:29], 1, v[26:27]
	v_mul_i32_i24_e32 v28, -12, v0
	s_add_i32 m0, s63, 0x400
	v_add_u32_e32 v0, s6, v0
	v_add_lshl_u32 v28, v28, v183, 3
	global_load_lds_dwordx4 v[26:27], off
	v_mad_i64_i32 v[26:27], s[16:17], v0, s7, v[24:25]
	v_ashrrev_i32_e32 v29, 31, v28
	v_mul_hi_u32 v0, v182, s18
	v_lshl_add_u64 v[26:27], v[28:29], 1, v[26:27]
	v_mul_i32_i24_e32 v28, -12, v0
	s_add_i32 m0, s63, 0x800
	v_add_u32_e32 v0, s6, v0
	v_add_lshl_u32 v28, v28, v182, 3
	global_load_lds_dwordx4 v[26:27], off
	v_mad_i64_i32 v[26:27], s[16:17], v0, s7, v[24:25]
	v_ashrrev_i32_e32 v29, 31, v28
	v_mul_hi_u32 v0, v180, s18
	v_lshl_add_u64 v[26:27], v[28:29], 1, v[26:27]
	v_mul_i32_i24_e32 v28, -12, v0
	s_add_i32 m0, s63, 0xc00
	v_add_u32_e32 v0, s6, v0
	v_add_lshl_u32 v28, v28, v180, 3
	global_load_lds_dwordx4 v[26:27], off
	v_mad_i64_i32 v[26:27], s[16:17], v0, s7, v[24:25]
	v_ashrrev_i32_e32 v29, 31, v28
	v_lshl_add_u64 v[26:27], v[28:29], 1, v[26:27]
	s_add_i32 m0, s63, 0x1000
	v_mul_hi_u32 v0, v179, s18
	global_load_lds_dwordx4 v[26:27], off
	v_mul_i32_i24_e32 v26, -12, v0
	v_add_u32_e32 v0, s6, v0
	v_mad_i64_i32 v[24:25], s[16:17], v0, s7, v[24:25]
	v_add_lshl_u32 v26, v26, v179, 3
	s_ashr_i32 s7, s6, 31
	v_ashrrev_i32_e32 v27, 31, v26
	s_add_i32 m0, s63, 0x1400
	s_lshl_b64 s[6:7], s[6:7], 7
	v_lshl_add_u64 v[24:25], v[26:27], 1, v[24:25]
	s_add_u32 s6, s46, s6
	global_load_lds_dwordx4 v[24:25], off
	s_addc_u32 s7, s47, s7
	v_mov_b32_e32 v177, v1
	s_mov_b32 m0, s59
	v_lshl_add_u64 v[24:25], s[6:7], 0, v[176:177]
	global_load_lds_dwordx4 v176, s[6:7]
	s_mov_b64 s[6:7], 0x400
	v_lshl_add_u64 v[26:27], v[24:25], 0, s[6:7]
	s_add_i32 m0, s59, 0x400
	s_mov_b64 s[6:7], 0x800
	global_load_lds_dwordx4 v[26:27], off
	v_lshl_add_u64 v[26:27], v[24:25], 0, s[6:7]
	s_mov_b64 s[6:7], 0xc00
	v_lshl_add_u64 v[24:25], v[24:25], 0, s[6:7]
	s_lshl_b32 s6, s57, 3
	s_add_i32 m0, s59, 0x800
	s_or_b32 s6, s6, s58
	global_load_lds_dwordx4 v[26:27], off
	s_add_i32 m0, s59, 0xc00
	s_mul_hi_i32 s7, s6, 0x186000
	s_mul_i32 s6, s6, 0x186000
	s_add_u32 s18, s14, s6
	s_addc_u32 s19, s15, s7
	s_add_u32 s6, s18, 0x3000
	s_mul_i32 s90, s58, 0x208000
	s_addc_u32 s7, s19, 0
	s_lshl_b64 s[16:17], s[90:91], 1
	s_add_u32 s16, s52, s16
	s_addc_u32 s17, s53, s17
	s_mul_i32 s21, s57, 0x4100
	global_load_lds_dwordx4 v[24:25], off
	s_mul_hi_i32 s20, s57, 0x4100
	s_add_u32 s16, s16, s21
	v_lshlrev_b64 v[24:25], 1, v[168:169]
	s_addc_u32 s17, s17, s20
	v_lshl_add_u64 v[26:27], s[6:7], 0, v[24:25]
	s_add_i32 m0, s72, 0x3400
	s_nop 0
	global_load_lds_dwordx4 v[26:27], off
	v_lshlrev_b64 v[26:27], 1, v[174:175]
	v_lshl_add_u64 v[28:29], s[6:7], 0, v[26:27]
	s_lshl_b32 s6, s61, 10
	s_add_i32 s20, s6, 0
	s_add_i32 m0, s20, 0x3400
	s_lshl_b32 s6, s60, 10
	global_load_lds_dwordx4 v[28:29], off
	v_lshl_add_u64 v[28:29], v[170:171], 1, s[16:17]
	v_lshl_add_u64 v[28:29], v[28:29], 0, s[10:11]
	s_add_i32 m0, s72, 0xf400
	s_add_i32 s6, s6, 0
	global_load_lds_dwordx4 v[28:29], off
	s_add_i32 m0, s6, 0xf400
	v_lshl_add_u64 v[28:29], v[172:173], 1, s[16:17]
	s_add_u32 s6, s18, 0x6000
	v_lshl_add_u64 v[28:29], v[28:29], 0, s[10:11]
	s_addc_u32 s7, s19, 0
	global_load_lds_dwordx4 v[28:29], off
	v_lshl_add_u64 v[24:25], s[6:7], 0, v[24:25]
	s_add_i32 m0, s72, 0x6800
	s_nop 0
	global_load_lds_dwordx4 v[24:25], off
	v_lshl_add_u64 v[24:25], s[6:7], 0, v[26:27]
	s_add_i32 m0, s20, 0x6800
	s_nop 0
	global_load_lds_dwordx4 v[24:25], off
	s_xor_b64 s[0:1], s[0:1], -1
	s_andn2_b64 vcc, exec, s[0:1]
	s_cbranch_vccnz .LBB0_25
	s_waitcnt vmcnt(16)
	s_branch .Lepi_z_ready

; __device__ __forceinline__ float xor32f(float v) { const auto rr = __builtin_amdgcn_permlane32_swap(__float_as_uint(v), __float_as_uint(v), false, false); const unsigned me = __float_as_uint(v); return __uint_as_float(rr[0] == me ? rr[1] : rr[0]); }
; __device__ __forceinline__ float siluf_(float z) { return z * sigmoidf_(z); }
; __device__ __forceinline__ u32x4 pack8(const f32x4& a, const f32x4& b) { u32x4 w; w.x = cvt_pk_bf16(a[0], a[1]); w.y = cvt_pk_bf16(a[2], a[3]); w.z = cvt_pk_bf16(b[0], b[1]); w.w = cvt_pk_bf16(b[2], b[3]); return w; }
; __device__ __forceinline__ void unpack8(const u32x4& w, float (&v)[8]) { v[0] = bf_lo(w.x); v[1] = bf_hi(w.x); v[2] = bf_lo(w.y); v[3] = bf_hi(w.y); v[4] = bf_lo(w.z); v[5] = bf_hi(w.z); v[6] = bf_lo(w.w); v[7] = bf_hi(w.w); }
; __device__ __forceinline__ void attn_unit(const Args& a, int l, int b, int h, int R0, bool special, LAS unsigned char* lds, float kb, int wv, bool pre, bool hasn, int nb, int nh, int nR0) {
;     ...
;     lsum += xor32f(lsum);
;     const float il = (lsum > 0.f) ? 1.0f / lsum : 0.f;
;     const bool st = !(special && wave >= 4);
;     bf16_t* prow = proj + (size_t)mq * PW + h * 64 + (hi ? 8 : 0);
;     u32x4 zw[4];
;     if (st) {
; #pragma unroll
;         for (int k = 0; k < 4; ++k) zw[k] = *(const u32x4*)(prow + C_ZM + 16 * k);
;     }
;     if (hasn) ATT_REQUEST(nb, nh, nR0);
;     ...
;     if (st) {
; #pragma unroll
;         for (int db = 0; db < 2; ++db)
; #pragma unroll
;             for (int gp = 0; gp < 2; ++gp) {
;                 const f32x16& o = db ? o1 : o0;
;                 float v[8];
; #pragma unroll
;                 for (int i = 0; i < 4; ++i) {
;                     const auto rr = __builtin_amdgcn_permlane32_swap(__float_as_uint(o[8 * gp + i]), __float_as_uint(o[8 * gp + 4 + i]), false, false);
;                     v[i] = __uint_as_float(rr[0]); v[4 + i] = __uint_as_float(rr[1]); }
;                 const int col = 32 * db + 16 * gp;
;                 float z[8]; unpack8(zw[2 * db + gp], z);
;                 f32x4 r0, r1;
; #pragma unroll
;                 for (int i = 0; i < 4; ++i) { r0[i] = v[i] * il * siluf_(z[i]); r1[i] = v[4 + i] * il * siluf_(z[4 + i]); }
;                 *(u32x4*)(prow + C_OZ + col) = pack8(r0, r1);
;             }
.Lepi_z_ready:
	v_cmp_eq_u32_e32 vcc, v17, v22
	v_lshlrev_b32_e32 v32, 16, v18
	v_and_b32_e32 v18, 0xffff0000, v18
	v_cndmask_b32_e32 v0, v17, v23, vcc
	v_add_f32_e32 v0, v22, v0
	v_div_scale_f32 v17, s[0:1], v0, v0, 1.0
	v_rcp_f32_e32 v22, v17
	v_and_b32_e32 v26, 0xffff0000, v20
	v_mov_b32_e32 v27, v133
	s_nop 1
	v_permlane32_swap_b32_e32 v129, v27
	v_fma_f32 v23, -v17, v22, 1.0
	v_fmac_f32_e32 v22, v23, v22
	v_div_scale_f32 v23, vcc, 1.0, v0, 1.0
	v_mul_f32_e32 v24, v23, v22
	v_fma_f32 v25, -v17, v24, v23
	v_fmac_f32_e32 v24, v25, v22
	v_fma_f32 v17, -v17, v24, v23
	v_div_fmas_f32 v17, v17, v22, v24
	v_div_fixup_f32 v17, v17, v0, 1.0
	v_cmp_lt_f32_e32 vcc, 0, v0
	v_mul_f32_e32 v0, 0xbfb8aa3b, v32
	v_exp_f32_e32 v0, v0
	v_lshlrev_b32_e32 v24, 16, v20
	v_mov_b32_e32 v25, v132
	s_nop 1
	v_permlane32_swap_b32_e32 v128, v25
	v_add_f32_e32 v0, 1.0, v0
	v_rcp_f32_e32 v22, v0
	v_mul_f32_e32 v0, 0xbfb8aa3b, v24
	v_exp_f32_e32 v0, v0
	v_cndmask_b32_e32 v23, 0, v17, vcc
	v_mov_b32_e32 v33, v128
	v_pk_mul_f32 v[32:33], v[22:23], v[32:33]
	v_add_f32_e32 v0, 1.0, v0
	v_rcp_f32_e32 v22, v0
	v_mul_f32_e32 v0, 0xbfb8aa3b, v18
	v_exp_f32_e32 v0, v0
	v_lshlrev_b32_e32 v34, 16, v19
	v_pk_mul_f32 v[24:25], v[22:23], v[24:25]
	v_and_b32_e32 v20, 0xffff0000, v19
	v_add_f32_e32 v0, 1.0, v0
	v_rcp_f32_e32 v22, v0
	v_mul_f32_e32 v0, 0xbfb8aa3b, v26
	v_exp_f32_e32 v0, v0
	v_mov_b32_e32 v19, v129
	v_pk_mul_f32 v[18:19], v[22:23], v[18:19]
	v_lshlrev_b32_e32 v28, 16, v21
	v_add_f32_e32 v0, 1.0, v0
	v_rcp_f32_e32 v22, v0
	v_mul_f32_e32 v0, 0xbfb8aa3b, v34
	v_exp_f32_e32 v0, v0
	v_mov_b32_e32 v29, v134
	v_pk_mul_f32 v[26:27], v[22:23], v[26:27]
	s_nop 0
	v_permlane32_swap_b32_e32 v130, v29
	v_add_f32_e32 v0, 1.0, v0
	v_rcp_f32_e32 v22, v0
	v_mul_f32_e32 v0, 0xbfb8aa3b, v28
	v_exp_f32_e32 v0, v0
	v_mov_b32_e32 v35, v130
	v_mul_f32_e32 v17, v32, v33
	v_pk_mul_f32 v[32:33], v[22:23], v[34:35]
	v_add_f32_e32 v0, 1.0, v0
	v_rcp_f32_e32 v22, v0
	v_mul_f32_e32 v0, 0xbfb8aa3b, v20
	v_exp_f32_e32 v0, v0
	v_and_b32_e32 v30, 0xffff0000, v21
	v_mul_f32_e32 v24, v24, v25
	v_mul_f32_e32 v25, v18, v19
	v_add_f32_e32 v0, 1.0, v0
	v_pk_mul_f32 v[18:19], v[22:23], v[28:29]
	v_rcp_f32_e32 v22, v0
	v_mul_f32_e32 v0, 0xbfb8aa3b, v30
	v_exp_f32_e32 v0, v0
	v_mov_b32_e32 v31, v135
	s_nop 1
	v_permlane32_swap_b32_e32 v131, v31
	v_mov_b32_e32 v21, v131
	v_add_f32_e32 v0, 1.0, v0
	v_pk_mul_f32 v[20:21], v[22:23], v[20:21]
	v_rcp_f32_e32 v22, v0
	v_mul_f32_e32 v26, v26, v27
	v_mul_f32_e32 v0, v32, v33
	v_mul_f32_e32 v27, v18, v19
	v_pk_mul_f32 v[18:19], v[22:23], v[30:31]
	v_lshlrev_b32_e32 v28, 16, v10
	v_mul_f32_e32 v20, v20, v21
	v_mul_f32_e32 v21, v18, v19
	v_cvt_pk_bf16_f32 v18, v17, v25
	v_cvt_pk_bf16_f32 v19, v0, v20
	v_mul_f32_e32 v0, 0xbfb8aa3b, v28
	v_exp_f32_e32 v0, v0
	v_cvt_pk_bf16_f32 v20, v24, v26
	v_cvt_pk_bf16_f32 v21, v27, v21
	global_store_dwordx4 v[14:15], v[18:21], off
	v_add_f32_e32 v0, 1.0, v0
	v_rcp_f32_e32 v22, v0
	v_lshlrev_b32_e32 v18, 16, v12
	v_mul_f32_e32 v0, 0xbfb8aa3b, v18
	v_exp_f32_e32 v0, v0
	v_mov_b32_e32 v19, v140
	s_nop 1
	v_permlane32_swap_b32_e32 v136, v19
	v_and_b32_e32 v10, 0xffff0000, v10
	v_mov_b32_e32 v29, v136
	v_add_f32_e32 v0, 1.0, v0
	v_pk_mul_f32 v[28:29], v[22:23], v[28:29]
	v_rcp_f32_e32 v22, v0
	v_mul_f32_e32 v0, 0xbfb8aa3b, v10
	v_exp_f32_e32 v0, v0
	v_and_b32_e32 v20, 0xffff0000, v12
	v_pk_mul_f32 v[18:19], v[22:23], v[18:19]
	v_mov_b32_e32 v21, v141
	v_add_f32_e32 v0, 1.0, v0
	v_rcp_f32_e32 v22, v0
	v_mul_f32_e32 v0, 0xbfb8aa3b, v20
	v_exp_f32_e32 v0, v0
	v_permlane32_swap_b32_e32 v137, v21
	v_lshlrev_b32_e32 v30, 16, v11
	v_and_b32_e32 v12, 0xffff0000, v11
	v_mov_b32_e32 v11, v137
	v_add_f32_e32 v0, 1.0, v0
	v_pk_mul_f32 v[10:11], v[22:23], v[10:11]
	v_rcp_f32_e32 v22, v0
	v_mul_f32_e32 v0, 0xbfb8aa3b, v30
	v_exp_f32_e32 v0, v0
	v_lshlrev_b32_e32 v24, 16, v13
	v_pk_mul_f32 v[20:21], v[22:23], v[20:21]
	v_mov_b32_e32 v25, v142
	v_add_f32_e32 v0, 1.0, v0
	v_rcp_f32_e32 v22, v0
	v_mul_f32_e32 v0, 0xbfb8aa3b, v24
	v_exp_f32_e32 v0, v0
	v_permlane32_swap_b32_e32 v138, v25
	v_mov_b32_e32 v31, v138
	v_add_f32_e32 v0, 1.0, v0
	v_mul_f32_e32 v17, v28, v29
	v_pk_mul_f32 v[28:29], v[22:23], v[30:31]
	v_rcp_f32_e32 v22, v0
	v_mul_f32_e32 v0, 0xbfb8aa3b, v12
	v_exp_f32_e32 v0, v0
	v_and_b32_e32 v26, 0xffff0000, v13
	v_mul_f32_e32 v18, v18, v19
	v_mul_f32_e32 v19, v10, v11
	v_add_f32_e32 v0, 1.0, v0
	v_pk_mul_f32 v[10:11], v[22:23], v[24:25]
	v_rcp_f32_e32 v22, v0
	v_mul_f32_e32 v0, 0xbfb8aa3b, v26
	v_exp_f32_e32 v0, v0
	v_mov_b32_e32 v27, v143
	s_nop 1
	v_permlane32_swap_b32_e32 v139, v27
	v_mov_b32_e32 v13, v139
	v_add_f32_e32 v0, 1.0, v0
	v_pk_mul_f32 v[12:13], v[22:23], v[12:13]
	v_rcp_f32_e32 v22, v0
	v_mul_f32_e32 v20, v20, v21
	v_mul_f32_e32 v0, v28, v29
; __device__ __forceinline__ float siluf_(float z) { return z * sigmoidf_(z); }
; __device__ __forceinline__ u32x4 pack8(const f32x4& a, const f32x4& b) { u32x4 w; w.x = cvt_pk_bf16(a[0], a[1]); w.y = cvt_pk_bf16(a[2], a[3]); w.z = cvt_pk_bf16(b[0], b[1]); w.w = cvt_pk_bf16(b[2], b[3]); return w; }
; __device__ __forceinline__ void unpack8(const u32x4& w, float (&v)[8]) { v[0] = bf_lo(w.x); v[1] = bf_hi(w.x); v[2] = bf_lo(w.y); v[3] = bf_hi(w.y); v[4] = bf_lo(w.z); v[5] = bf_hi(w.z); v[6] = bf_lo(w.w); v[7] = bf_hi(w.w); }
; __device__ __forceinline__ void attn_unit(const Args& a, int l, int b, int h, int R0, bool special, LAS unsigned char* lds, float kb, int wv, bool pre, bool hasn, int nb, int nh, int nR0) {
;     ...
;     if (st) {
; #pragma unroll
;         for (int db = 0; db < 2; ++db)
; #pragma unroll
;             for (int gp = 0; gp < 2; ++gp) {
;                 const f32x16& o = db ? o1 : o0;
;                 float v[8];
; #pragma unroll
;                 for (int i = 0; i < 4; ++i) {
;                     const auto rr = __builtin_amdgcn_permlane32_swap(__float_as_uint(o[8 * gp + i]), __float_as_uint(o[8 * gp + 4 + i]), false, false);
;                     v[i] = __uint_as_float(rr[0]); v[4 + i] = __uint_as_float(rr[1]); }
;                 const int col = 32 * db + 16 * gp;
;                 float z[8]; unpack8(zw[2 * db + gp], z);
;                 f32x4 r0, r1;
; #pragma unroll
;                 for (int i = 0; i < 4; ++i) { r0[i] = v[i] * il * siluf_(z[i]); r1[i] = v[4 + i] * il * siluf_(z[4 + i]); }
;                 *(u32x4*)(prow + C_OZ + col) = pack8(r0, r1);
;             }
	v_mul_f32_e32 v21, v10, v11
	v_pk_mul_f32 v[10:11], v[22:23], v[26:27]
	v_lshlrev_b32_e32 v24, 16, v6
	v_mul_f32_e32 v12, v12, v13
	v_mul_f32_e32 v13, v10, v11
	v_cvt_pk_bf16_f32 v10, v17, v19
	v_cvt_pk_bf16_f32 v11, v0, v12
	v_mul_f32_e32 v0, 0xbfb8aa3b, v24
	v_exp_f32_e32 v0, v0
	v_cvt_pk_bf16_f32 v12, v18, v20
	v_cvt_pk_bf16_f32 v13, v21, v13
	global_store_dwordx4 v[14:15], v[10:13], off offset:32
	v_add_f32_e32 v0, 1.0, v0
	v_rcp_f32_e32 v22, v0
	v_lshlrev_b32_e32 v10, 16, v8
	v_mul_f32_e32 v0, 0xbfb8aa3b, v10
	v_exp_f32_e32 v0, v0
	v_mov_b32_e32 v11, v116
	s_nop 1
	v_permlane32_swap_b32_e32 v112, v11
	v_and_b32_e32 v6, 0xffff0000, v6
	v_mov_b32_e32 v25, v112
	v_add_f32_e32 v0, 1.0, v0
	v_pk_mul_f32 v[24:25], v[22:23], v[24:25]
	v_rcp_f32_e32 v22, v0
	v_mul_f32_e32 v0, 0xbfb8aa3b, v6
	v_exp_f32_e32 v0, v0
	v_and_b32_e32 v12, 0xffff0000, v8
	v_pk_mul_f32 v[10:11], v[22:23], v[10:11]
	v_mov_b32_e32 v13, v117
	v_add_f32_e32 v0, 1.0, v0
	v_rcp_f32_e32 v22, v0
	v_mul_f32_e32 v0, 0xbfb8aa3b, v12
	v_exp_f32_e32 v0, v0
	v_permlane32_swap_b32_e32 v113, v13
	v_lshlrev_b32_e32 v26, 16, v7
	v_and_b32_e32 v8, 0xffff0000, v7
	v_mov_b32_e32 v7, v113
	v_add_f32_e32 v0, 1.0, v0
	v_pk_mul_f32 v[6:7], v[22:23], v[6:7]
	v_rcp_f32_e32 v22, v0
	v_mul_f32_e32 v0, 0xbfb8aa3b, v26
	v_exp_f32_e32 v0, v0
	v_lshlrev_b32_e32 v18, 16, v9
	v_pk_mul_f32 v[12:13], v[22:23], v[12:13]
	v_mov_b32_e32 v19, v118
	v_add_f32_e32 v0, 1.0, v0
	v_rcp_f32_e32 v22, v0
	v_mul_f32_e32 v0, 0xbfb8aa3b, v18
	v_exp_f32_e32 v0, v0
	v_permlane32_swap_b32_e32 v114, v19
	v_mov_b32_e32 v27, v114
	v_add_f32_e32 v0, 1.0, v0
	v_mul_f32_e32 v17, v24, v25
	v_pk_mul_f32 v[24:25], v[22:23], v[26:27]
	v_rcp_f32_e32 v22, v0
	v_mul_f32_e32 v0, 0xbfb8aa3b, v8
	v_exp_f32_e32 v0, v0
	v_and_b32_e32 v20, 0xffff0000, v9
	v_mul_f32_e32 v10, v10, v11
	v_mul_f32_e32 v11, v6, v7
	v_add_f32_e32 v0, 1.0, v0
	v_pk_mul_f32 v[6:7], v[22:23], v[18:19]
	v_rcp_f32_e32 v22, v0
	v_mul_f32_e32 v0, 0xbfb8aa3b, v20
	v_exp_f32_e32 v0, v0
	v_mov_b32_e32 v21, v119
	s_nop 1
	v_permlane32_swap_b32_e32 v115, v21
	v_mov_b32_e32 v9, v115
	v_add_f32_e32 v0, 1.0, v0
	v_pk_mul_f32 v[8:9], v[22:23], v[8:9]
	v_rcp_f32_e32 v22, v0
	v_mul_f32_e32 v12, v12, v13
	v_mul_f32_e32 v0, v24, v25
	v_mul_f32_e32 v13, v6, v7
	v_pk_mul_f32 v[6:7], v[22:23], v[20:21]
	v_lshlrev_b32_e32 v18, 16, v2
	v_mul_f32_e32 v8, v8, v9
	v_mul_f32_e32 v9, v6, v7
	v_cvt_pk_bf16_f32 v6, v17, v11
	v_cvt_pk_bf16_f32 v7, v0, v8
	v_mul_f32_e32 v0, 0xbfb8aa3b, v18
	v_exp_f32_e32 v0, v0
	v_cvt_pk_bf16_f32 v8, v10, v12
	v_cvt_pk_bf16_f32 v9, v13, v9
	global_store_dwordx4 v[14:15], v[6:9], off offset:64
	v_add_f32_e32 v0, 1.0, v0
	v_rcp_f32_e32 v22, v0
	v_lshlrev_b32_e32 v6, 16, v4
	v_mul_f32_e32 v0, 0xbfb8aa3b, v6
	v_exp_f32_e32 v0, v0
	v_mov_b32_e32 v7, v124
	s_nop 1
	v_permlane32_swap_b32_e32 v120, v7
	v_and_b32_e32 v2, 0xffff0000, v2
	v_mov_b32_e32 v19, v120
	v_add_f32_e32 v0, 1.0, v0
	v_pk_mul_f32 v[18:19], v[22:23], v[18:19]
	v_rcp_f32_e32 v22, v0
	v_mul_f32_e32 v0, 0xbfb8aa3b, v2
	v_exp_f32_e32 v0, v0
	v_and_b32_e32 v8, 0xffff0000, v4
	v_pk_mul_f32 v[6:7], v[22:23], v[6:7]
	v_mov_b32_e32 v9, v125
	v_add_f32_e32 v0, 1.0, v0
	v_rcp_f32_e32 v22, v0
	v_mul_f32_e32 v0, 0xbfb8aa3b, v8
	v_exp_f32_e32 v0, v0
	v_permlane32_swap_b32_e32 v121, v9
	v_lshlrev_b32_e32 v20, 16, v3
	v_and_b32_e32 v4, 0xffff0000, v3
	v_mov_b32_e32 v3, v121
	v_add_f32_e32 v0, 1.0, v0
	v_pk_mul_f32 v[2:3], v[22:23], v[2:3]
	v_rcp_f32_e32 v22, v0
	v_mul_f32_e32 v0, 0xbfb8aa3b, v20
	v_exp_f32_e32 v0, v0
	v_lshlrev_b32_e32 v10, 16, v5
	v_pk_mul_f32 v[8:9], v[22:23], v[8:9]
	v_mov_b32_e32 v11, v126
	v_add_f32_e32 v0, 1.0, v0
	v_rcp_f32_e32 v22, v0
	v_mul_f32_e32 v0, 0xbfb8aa3b, v10
	v_exp_f32_e32 v0, v0
	v_permlane32_swap_b32_e32 v122, v11
	v_mov_b32_e32 v21, v122
	v_add_f32_e32 v0, 1.0, v0
	v_mul_f32_e32 v17, v18, v19
	v_pk_mul_f32 v[18:19], v[22:23], v[20:21]
	v_rcp_f32_e32 v22, v0
	v_mul_f32_e32 v0, 0xbfb8aa3b, v4
	v_exp_f32_e32 v0, v0
	v_and_b32_e32 v12, 0xffff0000, v5
	v_mul_f32_e32 v6, v6, v7
	v_mul_f32_e32 v7, v2, v3
	v_add_f32_e32 v0, 1.0, v0
	v_pk_mul_f32 v[2:3], v[22:23], v[10:11]
	v_rcp_f32_e32 v22, v0
	v_mul_f32_e32 v0, 0xbfb8aa3b, v12
	v_exp_f32_e32 v0, v0
	v_mov_b32_e32 v13, v127
	s_nop 1
	v_permlane32_swap_b32_e32 v123, v13
	v_mov_b32_e32 v5, v123
	v_add_f32_e32 v0, 1.0, v0
	v_pk_mul_f32 v[4:5], v[22:23], v[4:5]
	v_rcp_f32_e32 v22, v0
	v_mul_f32_e32 v8, v8, v9
	v_mul_f32_e32 v9, v2, v3
	v_mul_f32_e32 v4, v4, v5
	v_pk_mul_f32 v[2:3], v[22:23], v[12:13]
	v_mul_f32_e32 v0, v18, v19
	v_mul_f32_e32 v5, v2, v3
	v_cvt_pk_bf16_f32 v2, v17, v7
	v_cvt_pk_bf16_f32 v3, v0, v4
	v_cvt_pk_bf16_f32 v4, v6, v8
	v_cvt_pk_bf16_f32 v5, v9, v5
	global_store_dwordx4 v[14:15], v[2:5], off offset:96
	s_branch .LBB0_25
